# grid-barrier root poll: 16 counter loads issued back-to-back with one wait (was 13 serial load+wait round trips) on top of v47
# baseline (speedup 1.0000x reference)
.LBB0_290:
	v_mov_b64_e32 v[12:13], s[38:39]
	v_mov_b64_e32 v[16:17], s[4:5]
	v_mov_b64_e32 v[14:15], s[6:7]
	flat_load_dword v1, v[12:13] offset:1024 sc1
	flat_load_dword v0, v[12:13] offset:1280 sc1
	flat_load_dword v2, v[12:13] offset:1536 sc1
	flat_load_dword v3, v[12:13] offset:1792 sc1
	flat_load_dword v4, v[12:13] offset:2048 sc1
	flat_load_dword v5, v[12:13] offset:2304 sc1
	flat_load_dword v6, v[12:13] offset:2560 sc1
	flat_load_dword v7, v[12:13] offset:2816 sc1
	flat_load_dword v8, v[12:13] offset:3072 sc1
	flat_load_dword v9, v[12:13] offset:3328 sc1
	flat_load_dword v10, v[12:13] offset:3584 sc1
	flat_load_dword v11, v[12:13] offset:3840 sc1
	flat_load_dword v12, v[16:17] sc1
	flat_load_dword v13, v[14:15] sc1
	v_mov_b64_e32 v[16:17], s[8:9]
	s_or_b64 s[18:19], s[18:19], exec
	flat_load_dword v14, v[16:17] sc1
	v_mov_b64_e32 v[16:17], s[10:11]
	s_or_b64 s[16:17], s[16:17], exec
	flat_load_dword v15, v[16:17] sc1
	s_waitcnt vmcnt(0) lgkmcnt(0)
	v_add3_u32 v16, v0, v1, v2
	v_add3_u32 v16, v16, v3, v4
	v_add3_u32 v16, v16, v5, v6
	v_add3_u32 v16, v16, v7, v8
	v_add3_u32 v16, v16, v9, v10
	v_add3_u32 v16, v16, v11, v12
	v_add3_u32 v16, v16, v13, v14
	v_add_u32_e32 v16, v16, v15
	v_cmp_ne_u32_e32 vcc, s61, v16
	s_and_saveexec_b64 s[20:21], vcc
	s_cbranch_execz .LBB0_289
	s_and_b32 s24, s30, 0xff
	s_mov_b64 s[22:23], -1
	s_cmp_eq_u32 s24, 0
	s_mov_b64 s[26:27], -1
	s_mov_b64 s[24:25], -1
	s_sleep 1
	s_cbranch_scc1 .LBB0_293
	s_and_saveexec_b64 s[28:29], s[26:27]
	s_cbranch_execz .LBB0_288
	s_branch .LBB0_296

.LBB0_374:
	v_mov_b64_e32 v[12:13], s[40:41]
	v_mov_b64_e32 v[16:17], s[4:5]
	v_mov_b64_e32 v[14:15], s[6:7]
	flat_load_dword v1, v[12:13] offset:1024 sc1
	flat_load_dword v0, v[12:13] offset:1280 sc1
	flat_load_dword v2, v[12:13] offset:1536 sc1
	flat_load_dword v3, v[12:13] offset:1792 sc1
	flat_load_dword v4, v[12:13] offset:2048 sc1
	flat_load_dword v5, v[12:13] offset:2304 sc1
	flat_load_dword v6, v[12:13] offset:2560 sc1
	flat_load_dword v7, v[12:13] offset:2816 sc1
	flat_load_dword v8, v[12:13] offset:3072 sc1
	flat_load_dword v9, v[12:13] offset:3328 sc1
	flat_load_dword v10, v[12:13] offset:3584 sc1
	flat_load_dword v11, v[12:13] offset:3840 sc1
	flat_load_dword v12, v[16:17] sc1
	flat_load_dword v13, v[14:15] sc1
	v_mov_b64_e32 v[16:17], s[8:9]
	s_or_b64 s[18:19], s[18:19], exec
	flat_load_dword v14, v[16:17] sc1
	v_mov_b64_e32 v[16:17], s[10:11]
	s_or_b64 s[16:17], s[16:17], exec
	flat_load_dword v15, v[16:17] sc1
	s_waitcnt vmcnt(0) lgkmcnt(0)
	v_add3_u32 v16, v0, v1, v2
	v_add3_u32 v16, v16, v3, v4
	v_add3_u32 v16, v16, v5, v6
	v_add3_u32 v16, v16, v7, v8
	v_add3_u32 v16, v16, v9, v10
	v_add3_u32 v16, v16, v11, v12
	v_add3_u32 v16, v16, v13, v14
	v_add_u32_e32 v16, v16, v15
	v_cmp_ne_u32_e32 vcc, s61, v16
	s_and_saveexec_b64 s[20:21], vcc
	s_cbranch_execz .LBB0_373
	s_and_b32 s24, s30, 0xff
	s_mov_b64 s[22:23], -1
	s_cmp_eq_u32 s24, 0
	s_mov_b64 s[26:27], -1
	s_mov_b64 s[24:25], -1
	s_sleep 1
	s_cbranch_scc1 .LBB0_377
	s_and_saveexec_b64 s[28:29], s[26:27]
	s_cbranch_execz .LBB0_372
	s_branch .LBB0_380
